# norm-phase output stores (H rows and residual fix-up rows) issued write-through (sc1) so the grid-barrier write-back has less to flush
# speedup vs baseline: 1.0049x; 1.0049x over previous
.LBB0_148:
	s_waitcnt vmcnt(0)
	v_pk_mul_f32 v[148:149], v[30:31], v[30:31]
	v_pk_mul_f32 v[150:151], v[32:33], v[32:33]
	v_add_f32_e32 v147, v148, v149
	v_add_f32_e32 v147, v147, v150
	v_pk_mul_f32 v[152:153], v[26:27], v[26:27]
	v_add_f32_e32 v147, v151, v147
	v_add_f32_e32 v147, v152, v147
	v_pk_mul_f32 v[154:155], v[28:29], v[28:29]
	v_add_f32_e32 v147, v153, v147
	v_add_f32_e32 v147, v154, v147
	v_pk_mul_f32 v[156:157], v[22:23], v[22:23]
	v_add_f32_e32 v147, v155, v147
	v_add_f32_e32 v147, v156, v147
	v_pk_mul_f32 v[158:159], v[24:25], v[24:25]
	v_add_f32_e32 v147, v157, v147
	v_add_f32_e32 v147, v158, v147
	v_pk_mul_f32 v[160:161], v[18:19], v[18:19]
	v_add_f32_e32 v147, v159, v147
	v_add_f32_e32 v147, v160, v147
	v_pk_mul_f32 v[162:163], v[20:21], v[20:21]
	v_add_f32_e32 v147, v161, v147
	v_add_f32_e32 v147, v162, v147
	v_pk_mul_f32 v[164:165], v[14:15], v[14:15]
	v_add_f32_e32 v147, v163, v147
	v_add_f32_e32 v147, v164, v147
	v_pk_mul_f32 v[166:167], v[16:17], v[16:17]
	v_add_f32_e32 v147, v165, v147
	v_add_f32_e32 v147, v166, v147
	v_pk_mul_f32 v[168:169], v[10:11], v[10:11]
	v_add_f32_e32 v147, v167, v147
	v_add_f32_e32 v147, v168, v147
	v_pk_mul_f32 v[170:171], v[12:13], v[12:13]
	v_add_f32_e32 v147, v169, v147
	v_add_f32_e32 v147, v170, v147
	v_pk_mul_f32 v[172:173], v[6:7], v[6:7]
	v_add_f32_e32 v147, v171, v147
	v_add_f32_e32 v147, v172, v147
	v_pk_mul_f32 v[174:175], v[8:9], v[8:9]
	v_add_f32_e32 v147, v173, v147
	v_add_f32_e32 v147, v174, v147
	v_pk_mul_f32 v[176:177], v[2:3], v[2:3]
	v_add_f32_e32 v147, v175, v147
	v_add_f32_e32 v147, v176, v147
	v_pk_mul_f32 v[178:179], v[4:5], v[4:5]
	v_add_f32_e32 v147, v177, v147
	v_add_f32_e32 v147, v178, v147
	v_add_f32_e32 v147, v179, v147
	s_add_i32 s6, s6, s82
	s_cmpk_lt_i32 s6, 0x2800
	v_add_f32_dpp v147, v147, v147 quad_perm:[1,0,3,2] row_mask:0xf bank_mask:0xf bound_ctrl:1
	s_nop 1
	v_add_f32_dpp v147, v147, v147 quad_perm:[2,3,0,1] row_mask:0xf bank_mask:0xf bound_ctrl:1
	s_nop 1
	v_add_f32_dpp v147, v147, v147 row_half_mirror row_mask:0xf bank_mask:0xf bound_ctrl:1
	s_nop 1
	v_add_f32_dpp v147, v147, v147 row_mirror row_mask:0xf bank_mask:0xf bound_ctrl:1
	ds_swizzle_b32 v148, v147 offset:swizzle(SWAP,16)
	s_waitcnt lgkmcnt(0)
	v_add_f32_e32 v147, v147, v148
	v_mov_b32_e32 v148, v147
	s_nop 1
	v_permlane32_swap_b32_e32 v147, v148
	v_add_f32_e32 v147, v147, v148
	v_fmamk_f32 v147, v147, 0x3a000000, v233
	v_rsq_f32_e32 v148, v147
	s_nop 0
	v_pk_mul_f32 v[26:27], v[26:27], v[148:149] op_sel_hi:[1,0]
	s_nop 0
	v_pk_mul_f32 v[26:27], v[110:111], v[26:27]
	v_pk_add_f32 v[110:111], v[114:115], 1.0 op_sel_hi:[1,0]
	v_pk_mul_f32 v[30:31], v[30:31], v[148:149] op_sel_hi:[1,0]
	v_pk_fma_f32 v[106:107], v[110:111], v[26:27], v[106:107]
	v_pk_mul_f32 v[26:27], v[32:33], v[148:149] op_sel_hi:[1,0]
	v_pk_add_f32 v[32:33], v[128:129], 1.0 op_sel_hi:[1,0]
	v_pk_mul_f32 v[26:27], v[124:125], v[26:27]
	v_pk_mul_f32 v[30:31], v[122:123], v[30:31]
	v_pk_add_f32 v[122:123], v[126:127], 1.0 op_sel_hi:[1,0]
	v_pk_fma_f32 v[32:33], v[32:33], v[26:27], v[120:121]
	v_pk_mul_f32 v[26:27], v[28:29], v[148:149] op_sel_hi:[1,0]
	v_pk_fma_f32 v[30:31], v[122:123], v[30:31], v[118:119]
	v_pk_mul_f32 v[26:27], v[112:113], v[26:27]
	v_pk_add_f32 v[28:29], v[116:117], 1.0 op_sel_hi:[1,0]
	v_pk_mul_f32 v[22:23], v[22:23], v[148:149] op_sel_hi:[1,0]
	v_pk_fma_f32 v[108:109], v[28:29], v[26:27], v[108:109]
	v_cvt_pk_bf16_f32 v26, v30, v31
	v_pk_mul_f32 v[22:23], v[98:99], v[22:23]
	v_pk_add_f32 v[30:31], v[102:103], 1.0 op_sel_hi:[1,0]
	v_pk_mul_f32 v[18:19], v[18:19], v[148:149] op_sel_hi:[1,0]
	v_pk_fma_f32 v[22:23], v[30:31], v[22:23], v[94:95]
	v_pk_mul_f32 v[18:19], v[86:87], v[18:19]
	v_pk_add_f32 v[30:31], v[90:91], 1.0 op_sel_hi:[1,0]
	v_pk_mul_f32 v[14:15], v[14:15], v[148:149] op_sel_hi:[1,0]
	v_pk_fma_f32 v[30:31], v[30:31], v[18:19], v[82:83]
	v_pk_mul_f32 v[18:19], v[24:25], v[148:149] op_sel_hi:[1,0]
	v_pk_add_f32 v[24:25], v[104:105], 1.0 op_sel_hi:[1,0]
	v_pk_mul_f32 v[18:19], v[100:101], v[18:19]
	v_cvt_pk_bf16_f32 v27, v32, v33
	v_pk_fma_f32 v[24:25], v[24:25], v[18:19], v[96:97]
	v_pk_mul_f32 v[18:19], v[20:21], v[148:149] op_sel_hi:[1,0]
	v_pk_add_f32 v[20:21], v[92:93], 1.0 op_sel_hi:[1,0]
	v_pk_mul_f32 v[18:19], v[88:89], v[18:19]
	v_pk_mul_f32 v[14:15], v[74:75], v[14:15]
	v_pk_fma_f32 v[32:33], v[20:21], v[18:19], v[84:85]
	v_cvt_pk_bf16_f32 v18, v22, v23
	v_pk_add_f32 v[22:23], v[78:79], 1.0 op_sel_hi:[1,0]
	v_pk_mul_f32 v[10:11], v[10:11], v[148:149] op_sel_hi:[1,0]
	v_pk_fma_f32 v[14:15], v[22:23], v[14:15], v[70:71]
	v_pk_mul_f32 v[10:11], v[62:63], v[10:11]
	v_pk_add_f32 v[22:23], v[66:67], 1.0 op_sel_hi:[1,0]
	v_pk_mul_f32 v[6:7], v[6:7], v[148:149] op_sel_hi:[1,0]
	v_pk_fma_f32 v[22:23], v[22:23], v[10:11], v[58:59]
	v_pk_mul_f32 v[10:11], v[16:17], v[148:149] op_sel_hi:[1,0]
	v_pk_add_f32 v[16:17], v[80:81], 1.0 op_sel_hi:[1,0]
	v_pk_mul_f32 v[10:11], v[76:77], v[10:11]
	v_cvt_pk_bf16_f32 v19, v24, v25
	v_pk_fma_f32 v[16:17], v[16:17], v[10:11], v[72:73]
	v_pk_mul_f32 v[10:11], v[12:13], v[148:149] op_sel_hi:[1,0]
	v_pk_add_f32 v[12:13], v[68:69], 1.0 op_sel_hi:[1,0]
	v_pk_mul_f32 v[10:11], v[64:65], v[10:11]
	v_pk_mul_f32 v[6:7], v[50:51], v[6:7]
	v_pk_fma_f32 v[24:25], v[12:13], v[10:11], v[60:61]
	v_cvt_pk_bf16_f32 v10, v14, v15
	v_pk_add_f32 v[14:15], v[54:55], 1.0 op_sel_hi:[1,0]
	v_pk_mul_f32 v[2:3], v[2:3], v[148:149] op_sel_hi:[1,0]
	v_pk_fma_f32 v[6:7], v[14:15], v[6:7], v[46:47]
	v_pk_mul_f32 v[2:3], v[38:39], v[2:3]
	v_pk_add_f32 v[14:15], v[42:43], 1.0 op_sel_hi:[1,0]
	v_cvt_pk_bf16_f32 v28, v106, v107
	v_pk_fma_f32 v[14:15], v[14:15], v[2:3], v[34:35]
	v_pk_mul_f32 v[2:3], v[8:9], v[148:149] op_sel_hi:[1,0]
	v_pk_add_f32 v[8:9], v[56:57], 1.0 op_sel_hi:[1,0]
	v_pk_mul_f32 v[2:3], v[52:53], v[2:3]
	v_cvt_pk_bf16_f32 v29, v108, v109
	v_pk_fma_f32 v[8:9], v[8:9], v[2:3], v[48:49]
	v_pk_mul_f32 v[2:3], v[4:5], v[148:149] op_sel_hi:[1,0]
	v_pk_add_f32 v[4:5], v[44:45], 1.0 op_sel_hi:[1,0]
	v_pk_mul_f32 v[2:3], v[40:41], v[2:3]
	v_cvt_pk_bf16_f32 v11, v16, v17
	v_pk_fma_f32 v[16:17], v[4:5], v[2:3], v[36:37]
	v_cvt_pk_bf16_f32 v20, v30, v31
	v_cvt_pk_bf16_f32 v21, v32, v33
	v_cvt_pk_bf16_f32 v12, v22, v23
	v_cvt_pk_bf16_f32 v13, v24, v25
	v_cvt_pk_bf16_f32 v2, v6, v7
	v_cvt_pk_bf16_f32 v3, v8, v9
	v_cvt_pk_bf16_f32 v4, v14, v15
	v_cvt_pk_bf16_f32 v5, v16, v17
	global_store_dwordx4 v[142:143], v[26:29], off sc1
	global_store_dwordx4 v[142:143], v[18:21], off offset:1024 sc1
	global_store_dwordx4 v[142:143], v[10:13], off offset:2048 sc1
	global_store_dwordx4 v[142:143], v[2:5], off offset:3072 sc1
	v_lshl_add_u64 v[142:143], v[142:143], 0, s[56:57]
	s_cbranch_scc0 .LBB0_157

.LBB0_155:
	s_lshl_b64 s[12:13], s[12:13], 2
	s_add_u32 s12, s16, s12
	s_addc_u32 s13, s17, s13
	s_add_u32 s14, s12, 0x2000
	s_addc_u32 s15, s13, 0
	global_load_dwordx4 v[110:113], v[132:133], off offset:16
	global_load_dwordx4 v[122:125], v[132:133], off
	global_load_dwordx4 v[106:109], v0, s[12:13] offset:16
	global_load_dwordx4 v[118:121], v0, s[12:13]
	global_load_dwordx4 v[114:117], v0, s[14:15] offset:16
	global_load_dwordx4 v[126:129], v0, s[14:15]
	global_load_dwordx4 v[86:89], v[132:133], off offset:2064
	global_load_dwordx4 v[98:101], v[132:133], off offset:2048
	global_load_dwordx4 v[82:85], v0, s[12:13] offset:2064
	global_load_dwordx4 v[94:97], v0, s[12:13] offset:2048
	global_load_dwordx4 v[90:93], v144, s[14:15] offset:16
	global_load_dwordx4 v[102:105], v144, s[14:15]
	global_load_dwordx4 v[62:65], v[134:135], off offset:16
	global_load_dwordx4 v[74:77], v[134:135], off
	global_load_dwordx4 v[58:61], v145, s[12:13] offset:16
	global_load_dwordx4 v[70:73], v145, s[12:13]
	global_load_dwordx4 v[66:69], v145, s[14:15] offset:16
	global_load_dwordx4 v[78:81], v145, s[14:15]
	global_load_dwordx4 v[38:41], v[136:137], off offset:16
	global_load_dwordx4 v[50:53], v[136:137], off
	global_load_dwordx4 v[34:37], v146, s[12:13] offset:16
	global_load_dwordx4 v[46:49], v146, s[12:13]
	global_load_dwordx4 v[42:45], v146, s[14:15] offset:16
	global_load_dwordx4 v[54:57], v146, s[14:15]
	s_and_b64 vcc, exec, s[4:5]
	s_cbranch_vccnz .LBB0_148
	s_mov_b32 s7, s47
	s_lshl_b64 s[4:5], s[6:7], 12
	s_waitcnt vmcnt(0)
	v_cvt_pk_bf16_f32 v148, v30, v31
	v_cvt_pk_bf16_f32 v149, v32, v33
	v_cvt_pk_bf16_f32 v150, v26, v27
	v_cvt_pk_bf16_f32 v151, v28, v29
	v_lshl_add_u64 v[152:153], v[140:141], 0, s[4:5]
	global_store_dwordx4 v[152:153], v[148:151], off sc1
	s_nop 1
	v_cvt_pk_bf16_f32 v148, v22, v23
	v_cvt_pk_bf16_f32 v149, v24, v25
	v_cvt_pk_bf16_f32 v150, v18, v19
	v_cvt_pk_bf16_f32 v151, v20, v21
	global_store_dwordx4 v[152:153], v[148:151], off offset:1024 sc1
	s_nop 1
	v_cvt_pk_bf16_f32 v148, v14, v15
	v_cvt_pk_bf16_f32 v149, v16, v17
	v_cvt_pk_bf16_f32 v150, v10, v11
	v_cvt_pk_bf16_f32 v151, v12, v13
	global_store_dwordx4 v[152:153], v[148:151], off offset:2048 sc1
	s_nop 1
	v_cvt_pk_bf16_f32 v148, v6, v7
	v_cvt_pk_bf16_f32 v149, v8, v9
	v_cvt_pk_bf16_f32 v150, v2, v3
	v_cvt_pk_bf16_f32 v151, v4, v5
	global_store_dwordx4 v[152:153], v[148:151], off offset:3072 sc1
	s_branch .LBB0_148

.LBB0_1029:
	v_pk_mul_f32 v[150:151], v[30:31], v[30:31]
	v_pk_mul_f32 v[152:153], v[32:33], v[32:33]
	v_add_f32_e32 v149, v150, v151
	v_add_f32_e32 v149, v149, v152
	v_pk_mul_f32 v[154:155], v[26:27], v[26:27]
	v_add_f32_e32 v149, v153, v149
	v_add_f32_e32 v149, v154, v149
	v_pk_mul_f32 v[156:157], v[28:29], v[28:29]
	v_add_f32_e32 v149, v155, v149
	v_add_f32_e32 v149, v156, v149
	v_pk_mul_f32 v[158:159], v[22:23], v[22:23]
	v_add_f32_e32 v149, v157, v149
	v_add_f32_e32 v149, v158, v149
	v_pk_mul_f32 v[160:161], v[24:25], v[24:25]
	v_add_f32_e32 v149, v159, v149
	v_add_f32_e32 v149, v160, v149
	v_pk_mul_f32 v[162:163], v[18:19], v[18:19]
	v_add_f32_e32 v149, v161, v149
	v_add_f32_e32 v149, v162, v149
	v_pk_mul_f32 v[164:165], v[20:21], v[20:21]
	v_add_f32_e32 v149, v163, v149
	v_add_f32_e32 v149, v164, v149
	v_pk_mul_f32 v[166:167], v[14:15], v[14:15]
	v_add_f32_e32 v149, v165, v149
	v_add_f32_e32 v149, v166, v149
	v_pk_mul_f32 v[168:169], v[16:17], v[16:17]
	v_add_f32_e32 v149, v167, v149
	v_add_f32_e32 v149, v168, v149
	v_pk_mul_f32 v[170:171], v[10:11], v[10:11]
	v_add_f32_e32 v149, v169, v149
	v_add_f32_e32 v149, v170, v149
	v_pk_mul_f32 v[172:173], v[12:13], v[12:13]
	v_add_f32_e32 v149, v171, v149
	v_add_f32_e32 v149, v172, v149
	v_pk_mul_f32 v[174:175], v[6:7], v[6:7]
	v_add_f32_e32 v149, v173, v149
	v_add_f32_e32 v149, v174, v149
	v_pk_mul_f32 v[176:177], v[8:9], v[8:9]
	v_add_f32_e32 v149, v175, v149
	v_add_f32_e32 v149, v176, v149
	v_pk_mul_f32 v[178:179], v[2:3], v[2:3]
	v_add_f32_e32 v149, v177, v149
	v_add_f32_e32 v149, v178, v149
	v_pk_mul_f32 v[180:181], v[4:5], v[4:5]
	v_add_f32_e32 v149, v179, v149
	v_add_f32_e32 v149, v180, v149
	v_add_f32_e32 v149, v181, v149
	s_add_i32 s2, s2, s82
	s_cmpk_lt_i32 s2, 0x2800
	v_add_f32_dpp v149, v149, v149 quad_perm:[1,0,3,2] row_mask:0xf bank_mask:0xf bound_ctrl:1
	s_nop 1
	v_add_f32_dpp v149, v149, v149 quad_perm:[2,3,0,1] row_mask:0xf bank_mask:0xf bound_ctrl:1
	s_nop 1
	v_add_f32_dpp v149, v149, v149 row_half_mirror row_mask:0xf bank_mask:0xf bound_ctrl:1
	s_nop 1
	v_add_f32_dpp v149, v149, v149 row_mirror row_mask:0xf bank_mask:0xf bound_ctrl:1
	ds_swizzle_b32 v150, v149 offset:swizzle(SWAP,16)
	s_waitcnt lgkmcnt(0)
	v_add_f32_e32 v149, v149, v150
	v_mov_b32_e32 v150, v149
	s_nop 1
	v_permlane32_swap_b32_e32 v149, v150
	v_add_f32_e32 v149, v149, v150
	v_fmamk_f32 v149, v149, 0x3a000000, v233
	v_rsq_f32_e32 v150, v149
	s_nop 0
	v_pk_mul_f32 v[26:27], v[26:27], v[150:151] op_sel_hi:[1,0]
	s_nop 0
	s_waitcnt vmcnt(0)
	v_pk_mul_f32 v[26:27], v[110:111], v[26:27]
	v_pk_add_f32 v[110:111], v[114:115], 1.0 op_sel_hi:[1,0]
	v_pk_mul_f32 v[30:31], v[30:31], v[150:151] op_sel_hi:[1,0]
	v_pk_fma_f32 v[106:107], v[110:111], v[26:27], v[106:107]
	v_pk_mul_f32 v[26:27], v[32:33], v[150:151] op_sel_hi:[1,0]
	v_pk_add_f32 v[32:33], v[128:129], 1.0 op_sel_hi:[1,0]
	v_pk_mul_f32 v[26:27], v[124:125], v[26:27]
	v_pk_mul_f32 v[30:31], v[122:123], v[30:31]
	v_pk_add_f32 v[122:123], v[126:127], 1.0 op_sel_hi:[1,0]
	v_pk_fma_f32 v[32:33], v[32:33], v[26:27], v[120:121]
	v_pk_mul_f32 v[26:27], v[28:29], v[150:151] op_sel_hi:[1,0]
	v_pk_fma_f32 v[30:31], v[122:123], v[30:31], v[118:119]
	v_pk_mul_f32 v[26:27], v[112:113], v[26:27]
	v_pk_add_f32 v[28:29], v[116:117], 1.0 op_sel_hi:[1,0]
	v_pk_mul_f32 v[22:23], v[22:23], v[150:151] op_sel_hi:[1,0]
	v_pk_fma_f32 v[108:109], v[28:29], v[26:27], v[108:109]
	v_cvt_pk_bf16_f32 v26, v30, v31
	v_pk_mul_f32 v[22:23], v[98:99], v[22:23]
	v_pk_add_f32 v[30:31], v[102:103], 1.0 op_sel_hi:[1,0]
	v_pk_mul_f32 v[18:19], v[18:19], v[150:151] op_sel_hi:[1,0]
	v_pk_fma_f32 v[22:23], v[30:31], v[22:23], v[94:95]
	v_pk_mul_f32 v[18:19], v[86:87], v[18:19]
	v_pk_add_f32 v[30:31], v[90:91], 1.0 op_sel_hi:[1,0]
	v_pk_mul_f32 v[14:15], v[14:15], v[150:151] op_sel_hi:[1,0]
	v_pk_fma_f32 v[30:31], v[30:31], v[18:19], v[82:83]
	v_pk_mul_f32 v[18:19], v[24:25], v[150:151] op_sel_hi:[1,0]
	v_pk_add_f32 v[24:25], v[104:105], 1.0 op_sel_hi:[1,0]
	v_pk_mul_f32 v[18:19], v[100:101], v[18:19]
	v_cvt_pk_bf16_f32 v27, v32, v33
	v_pk_fma_f32 v[24:25], v[24:25], v[18:19], v[96:97]
	v_pk_mul_f32 v[18:19], v[20:21], v[150:151] op_sel_hi:[1,0]
	v_pk_add_f32 v[20:21], v[92:93], 1.0 op_sel_hi:[1,0]
	v_pk_mul_f32 v[18:19], v[88:89], v[18:19]
	v_pk_mul_f32 v[14:15], v[74:75], v[14:15]
	v_pk_fma_f32 v[32:33], v[20:21], v[18:19], v[84:85]
	v_cvt_pk_bf16_f32 v18, v22, v23
	v_pk_add_f32 v[22:23], v[78:79], 1.0 op_sel_hi:[1,0]
	v_pk_mul_f32 v[10:11], v[10:11], v[150:151] op_sel_hi:[1,0]
	v_pk_fma_f32 v[14:15], v[22:23], v[14:15], v[70:71]
	v_pk_mul_f32 v[10:11], v[62:63], v[10:11]
	v_pk_add_f32 v[22:23], v[66:67], 1.0 op_sel_hi:[1,0]
	v_pk_mul_f32 v[6:7], v[6:7], v[150:151] op_sel_hi:[1,0]
	v_pk_fma_f32 v[22:23], v[22:23], v[10:11], v[58:59]
	v_pk_mul_f32 v[10:11], v[16:17], v[150:151] op_sel_hi:[1,0]
	v_pk_add_f32 v[16:17], v[80:81], 1.0 op_sel_hi:[1,0]
	v_pk_mul_f32 v[10:11], v[76:77], v[10:11]
	v_cvt_pk_bf16_f32 v19, v24, v25
	v_pk_fma_f32 v[16:17], v[16:17], v[10:11], v[72:73]
	v_pk_mul_f32 v[10:11], v[12:13], v[150:151] op_sel_hi:[1,0]
	v_pk_add_f32 v[12:13], v[68:69], 1.0 op_sel_hi:[1,0]
	v_pk_mul_f32 v[10:11], v[64:65], v[10:11]
	v_pk_mul_f32 v[6:7], v[50:51], v[6:7]
	v_pk_fma_f32 v[24:25], v[12:13], v[10:11], v[60:61]
	v_cvt_pk_bf16_f32 v10, v14, v15
	v_pk_add_f32 v[14:15], v[54:55], 1.0 op_sel_hi:[1,0]
	v_pk_mul_f32 v[2:3], v[2:3], v[150:151] op_sel_hi:[1,0]
	v_pk_fma_f32 v[6:7], v[14:15], v[6:7], v[46:47]
	v_pk_mul_f32 v[2:3], v[38:39], v[2:3]
	v_pk_add_f32 v[14:15], v[42:43], 1.0 op_sel_hi:[1,0]
	v_cvt_pk_bf16_f32 v28, v106, v107
	v_pk_fma_f32 v[14:15], v[14:15], v[2:3], v[34:35]
	v_pk_mul_f32 v[2:3], v[8:9], v[150:151] op_sel_hi:[1,0]
	v_pk_add_f32 v[8:9], v[56:57], 1.0 op_sel_hi:[1,0]
	v_pk_mul_f32 v[2:3], v[52:53], v[2:3]
	v_cvt_pk_bf16_f32 v29, v108, v109
	v_pk_fma_f32 v[8:9], v[8:9], v[2:3], v[48:49]
	v_pk_mul_f32 v[2:3], v[4:5], v[150:151] op_sel_hi:[1,0]
	v_pk_add_f32 v[4:5], v[44:45], 1.0 op_sel_hi:[1,0]
	v_pk_mul_f32 v[2:3], v[40:41], v[2:3]
	v_cvt_pk_bf16_f32 v11, v16, v17
	v_pk_fma_f32 v[16:17], v[4:5], v[2:3], v[36:37]
	v_cvt_pk_bf16_f32 v20, v30, v31
	v_cvt_pk_bf16_f32 v21, v32, v33
	v_cvt_pk_bf16_f32 v12, v22, v23
	v_cvt_pk_bf16_f32 v13, v24, v25
	v_cvt_pk_bf16_f32 v2, v6, v7
	v_cvt_pk_bf16_f32 v3, v8, v9
	v_cvt_pk_bf16_f32 v4, v14, v15
	v_cvt_pk_bf16_f32 v5, v16, v17
	global_store_dwordx4 v[144:145], v[26:29], off sc1
	global_store_dwordx4 v[144:145], v[18:21], off offset:1024 sc1
	global_store_dwordx4 v[144:145], v[10:13], off offset:2048 sc1
	global_store_dwordx4 v[144:145], v[2:5], off offset:3072 sc1
	v_lshl_add_u64 v[144:145], v[144:145], 0, s[56:57]
	s_cbranch_scc0 .LBB0_1038

.LBB0_1036:
	s_lshl_b64 s[8:9], s[8:9], 2
	s_add_u32 s8, s16, s8
	s_addc_u32 s9, s17, s9
	s_add_u32 s10, s8, 0x2000
	s_addc_u32 s11, s9, 0
	global_load_dwordx4 v[110:113], v[132:133], off offset:16
	global_load_dwordx4 v[122:125], v[132:133], off
	global_load_dwordx4 v[106:109], v0, s[8:9] offset:16
	global_load_dwordx4 v[118:121], v0, s[8:9]
	global_load_dwordx4 v[114:117], v0, s[10:11] offset:16
	global_load_dwordx4 v[126:129], v0, s[10:11]
	global_load_dwordx4 v[86:89], v[132:133], off offset:2064
	global_load_dwordx4 v[98:101], v[132:133], off offset:2048
	global_load_dwordx4 v[82:85], v0, s[8:9] offset:2064
	global_load_dwordx4 v[94:97], v0, s[8:9] offset:2048
	global_load_dwordx4 v[90:93], v146, s[10:11] offset:16
	global_load_dwordx4 v[102:105], v146, s[10:11]
	global_load_dwordx4 v[62:65], v[134:135], off offset:16
	global_load_dwordx4 v[74:77], v[134:135], off
	global_load_dwordx4 v[58:61], v147, s[8:9] offset:16
	global_load_dwordx4 v[70:73], v147, s[8:9]
	global_load_dwordx4 v[66:69], v147, s[10:11] offset:16
	global_load_dwordx4 v[78:81], v147, s[10:11]
	global_load_dwordx4 v[38:41], v[136:137], off offset:16
	global_load_dwordx4 v[50:53], v[136:137], off
	global_load_dwordx4 v[34:37], v148, s[8:9] offset:16
	global_load_dwordx4 v[46:49], v148, s[8:9]
	global_load_dwordx4 v[42:45], v148, s[10:11] offset:16
	global_load_dwordx4 v[54:57], v148, s[10:11]
	s_and_b64 vcc, exec, s[4:5]
	s_cbranch_vccnz .LBB0_1029
	s_mov_b32 s3, s47
	s_lshl_b64 s[4:5], s[2:3], 12
	s_waitcnt vmcnt(0)
	v_cvt_pk_bf16_f32 v150, v30, v31
	v_cvt_pk_bf16_f32 v151, v32, v33
	v_cvt_pk_bf16_f32 v152, v26, v27
	v_cvt_pk_bf16_f32 v153, v28, v29
	v_lshl_add_u64 v[154:155], v[142:143], 0, s[4:5]
	global_store_dwordx4 v[154:155], v[150:153], off sc1
	s_nop 1
	v_cvt_pk_bf16_f32 v150, v22, v23
	v_cvt_pk_bf16_f32 v151, v24, v25
	v_cvt_pk_bf16_f32 v152, v18, v19
	v_cvt_pk_bf16_f32 v153, v20, v21
	global_store_dwordx4 v[154:155], v[150:153], off offset:1024 sc1
	s_nop 1
	v_cvt_pk_bf16_f32 v150, v14, v15
	v_cvt_pk_bf16_f32 v151, v16, v17
	v_cvt_pk_bf16_f32 v152, v10, v11
	v_cvt_pk_bf16_f32 v153, v12, v13
	global_store_dwordx4 v[154:155], v[150:153], off offset:2048 sc1
	s_nop 1
	v_cvt_pk_bf16_f32 v150, v6, v7
	v_cvt_pk_bf16_f32 v151, v8, v9
	v_cvt_pk_bf16_f32 v152, v2, v3
	v_cvt_pk_bf16_f32 v153, v4, v5
	global_store_dwordx4 v[154:155], v[150:153], off offset:3072 sc1
	s_nop 1
	s_branch .LBB0_1029
